# layer-1 W2 conversion moved from P1(l1) to the head of the dynamic phase P5(l1) (88 WGs without an F2 unit, before they enter the GLA-output queue); P1(l1) keeps only its first tile
# baseline (speedup 1.0000x reference)
; #define WT_LOAD() do { _Pragma("unroll") for (int i = 0; i < 16; ++i) rg[i] = sp ? sp[(size_t)(k0 + kq + i * 8) * ld] : 0.f; } while (0)
; __device__ __forceinline__ void phase_weights(int wv, const Params& p, int l, LAS unsigned char* lds, int first, int stride) {
;     ...
;     while (ti < 1536) {
;         bf16_t* cdst = dst + (size_t)n0 * K + k0; const int cK = K;
;         __syncthreads();
; #pragma unroll
;         for (int i = 0; i < 16; ++i) tile[(kq + i * 8) * 65 + nl] = rg[i];
;         ti += stride;
;         if (ti < 1536) { WT_DECODE(ti); WT_LOAD(); }
.LBB0_232:
	s_add_i32 s46, s46, s1
	s_cmpk_lg_u32 s44, 0x100
	s_cbranch_scc1 .Lws_done
	v_readlane_b32 s101, v255, 22
	s_cmp_eq_u32 s101, 1
	s_movk_i32 s101, 0x4a0
	s_cbranch_scc0 .Lws_chk
	s_movk_i32 s101, 0x160
.Lws_chk:
	s_cmp_lt_i32 s46, s101
	s_cbranch_scc1 .Lws_done
	s_movk_i32 s46, 0x600

; __device__ __forceinline__ unsigned pk_bf16(float lo, float hi) { unsigned r; asm volatile("v_cvt_pk_bf16_f32 %0, %1, %2" : "=v"(r) : "v"(lo), "v"(hi)); return r; }
; #define WT_LOAD() do { _Pragma("unroll") for (int i = 0; i < 16; ++i) rg[i] = sp ? sp[(size_t)(k0 + kq + i * 8) * ld] : 0.f; } while (0)
; __device__ __forceinline__ void phase_weights(int wv, const Params& p, int l, LAS unsigned char* lds, int first, int stride) {
;     ...
;     if (ti < 1536) { WT_DECODE(ti); WT_LOAD(); }
;     while (ti < 1536) {
;         bf16_t* cdst = dst + (size_t)n0 * K + k0; const int cK = K;
;         __syncthreads();
; #pragma unroll
;         for (int i = 0; i < 16; ++i) tile[(kq + i * 8) * 65 + nl] = rg[i];
;         ti += stride;
;         if (ti < 1536) { WT_DECODE(ti); WT_LOAD(); }
;         __syncthreads();
;         { const int nn = tid >> 3, ks = tid & 7; float v[16];
; #pragma unroll
;             for (int j = 0; j < 16; ++j) v[j] = tile[(ks * 16 + j) * 65 + nn];
;             u32x4 w0, w1; w0.x = pk_bf16(v[0], v[1]); w0.y = pk_bf16(v[2], v[3]); w0.z = pk_bf16(v[4], v[5]); w0.w = pk_bf16(v[6], v[7]);
;             w1.x = pk_bf16(v[8], v[9]); w1.y = pk_bf16(v[10], v[11]); w1.z = pk_bf16(v[12], v[13]); w1.w = pk_bf16(v[14], v[15]);
;             bf16_t* o = cdst + (size_t)nn * cK + ks * 16; *(u32x4*)o = w0; *(u32x4*)(o + 8) = w1; }
.Lgb_done_4:
.LBB0_939:
	s_or_b64 exec, exec, s[6:7]
	v_writelane_b32 v255, s24, 63
	v_readlane_b32 s24, v255, 3
	s_cmpk_lt_u32 s24, 64
	s_cbranch_scc1 .Lew_end_p5
	s_cmpk_lg_u32 s44, 0x100
	s_cbranch_scc1 .Lew_end_p5
	v_readlane_b32 s24, v255, 22
	s_cmp_lg_u32 s24, 1
	s_cbranch_scc1 .Lew_end_p5
	v_writelane_b32 v255, s3, 43
	v_writelane_b32 v255, s6, 44
	v_writelane_b32 v255, s7, 45
	v_writelane_b32 v255, s14, 46
	v_writelane_b32 v255, s15, 47
	v_writelane_b32 v255, s16, 48
	v_writelane_b32 v255, s17, 49
	v_writelane_b32 v255, s18, 50
	v_writelane_b32 v255, s19, 51
	v_writelane_b32 v255, s22, 52
	v_writelane_b32 v255, s23, 53
	v_writelane_b32 v255, s26, 54
	v_writelane_b32 v255, s27, 55
	v_writelane_b32 v255, s30, 56
	v_writelane_b32 v255, s31, 57
	v_writelane_b32 v255, s36, 58
	v_writelane_b32 v255, s37, 59
	s_load_dwordx2 s[14:15], s[90:91], 0x98
	s_load_dwordx2 s[16:17], s[90:91], 0xa8
	v_mbcnt_lo_u32_b32 v2, -1, 0
	v_mbcnt_hi_u32_b32 v2, -1, v2
	v_and_b32_e32 v3, 15, v2
	v_lshrrev_b32_e32 v6, 4, v2
	v_lshlrev_b32_e32 v12, 4, v3
	v_lshl_add_u32 v12, v6, 16, v12
	v_add_u32_e32 v12, 0xb00000, v12
	v_mov_b32_e32 v13, 0
	v_mul_u32_u24_e32 v10, 0x5800, v3
	v_lshl_add_u32 v10, v6, 5, v10
	s_waitcnt lgkmcnt(0)
	v_mov_b32_e32 v4, s14
	v_mov_b32_e32 v5, s15
	v_lshl_add_u64 v[4:5], v[4:5], 0, v[12:13]
	s_add_u32 s16, s16, 0xc04c000
	s_addc_u32 s17, s17, 0
	v_readlane_b32 s24, v255, 7
	s_lshr_b32 s24, s24, 6
	v_readlane_b32 s3, v255, 3
	s_sub_i32 s3, s3, 64
	s_lshl_b32 s3, s3, 3
	s_add_i32 s3, s3, s24
.Lew_loop_p5:
	s_cmpk_gt_u32 s3, 0x2bf
	s_cbranch_scc1 .Lew_rest_p5
	s_mul_hi_u32 s6, s3, 0x5d1745e
	s_mul_i32 s7, s6, 44
	s_sub_i32 s7, s3, s7
	s_lshl_b32 s22, s7, 18
	s_lshl_b32 s24, s6, 8
	s_add_i32 s22, s22, s24
	s_mov_b32 s23, 0
	s_mul_i32 s24, s6, 0x58000
	s_lshl_b32 s7, s7, 7
	s_add_i32 s24, s24, s7
	s_add_u32 s18, s16, s24
	s_addc_u32 s19, s17, 0
	s_add_u32 s26, s18, 0x1600
	s_addc_u32 s27, s19, 0
	s_add_u32 s30, s26, 0x1600
	s_addc_u32 s31, s27, 0
	s_add_u32 s36, s30, 0x1600
	s_addc_u32 s37, s31, 0
	v_lshl_add_u64 v[6:7], s[22:23], 0, v[4:5]
	global_load_dwordx4 v[20:23], v[6:7], off
	s_add_u32 s22, s22, 0x1000
	v_lshl_add_u64 v[8:9], s[22:23], 0, v[4:5]
	global_load_dwordx4 v[24:27], v[8:9], off
	s_add_u32 s22, s22, 0x1000
	v_lshl_add_u64 v[6:7], s[22:23], 0, v[4:5]
	global_load_dwordx4 v[28:31], v[6:7], off
	s_add_u32 s22, s22, 0x1000
	v_lshl_add_u64 v[8:9], s[22:23], 0, v[4:5]
	global_load_dwordx4 v[32:35], v[8:9], off
	s_add_u32 s22, s22, 0x1000
	v_lshl_add_u64 v[6:7], s[22:23], 0, v[4:5]
	global_load_dwordx4 v[36:39], v[6:7], off
	s_add_u32 s22, s22, 0x1000
	v_lshl_add_u64 v[8:9], s[22:23], 0, v[4:5]
	global_load_dwordx4 v[40:43], v[8:9], off
	s_add_u32 s22, s22, 0x1000
	v_lshl_add_u64 v[6:7], s[22:23], 0, v[4:5]
	global_load_dwordx4 v[44:47], v[6:7], off
	s_add_u32 s22, s22, 0x1000
	v_lshl_add_u64 v[8:9], s[22:23], 0, v[4:5]
	global_load_dwordx4 v[48:51], v[8:9], off
	s_add_u32 s22, s22, 0x1000
	v_lshl_add_u64 v[6:7], s[22:23], 0, v[4:5]
	global_load_dwordx4 v[52:55], v[6:7], off
	s_add_u32 s22, s22, 0x1000
	v_lshl_add_u64 v[8:9], s[22:23], 0, v[4:5]
	global_load_dwordx4 v[56:59], v[8:9], off
	s_add_u32 s22, s22, 0x1000
	v_lshl_add_u64 v[6:7], s[22:23], 0, v[4:5]
	global_load_dwordx4 v[60:63], v[6:7], off
	s_add_u32 s22, s22, 0x1000
	v_lshl_add_u64 v[8:9], s[22:23], 0, v[4:5]
	global_load_dwordx4 v[64:67], v[8:9], off
	s_add_u32 s22, s22, 0x1000
	v_lshl_add_u64 v[6:7], s[22:23], 0, v[4:5]
	global_load_dwordx4 v[68:71], v[6:7], off
	s_add_u32 s22, s22, 0x1000
	v_lshl_add_u64 v[8:9], s[22:23], 0, v[4:5]
	global_load_dwordx4 v[72:75], v[8:9], off
	s_add_u32 s22, s22, 0x1000
	v_lshl_add_u64 v[6:7], s[22:23], 0, v[4:5]
	global_load_dwordx4 v[76:79], v[6:7], off
	s_add_u32 s22, s22, 0x1000
	v_lshl_add_u64 v[8:9], s[22:23], 0, v[4:5]
	global_load_dwordx4 v[80:83], v[8:9], off
	s_add_u32 s22, s22, 0x1000
	s_waitcnt vmcnt(0)
	v_cvt_pk_bf16_f32 v84, v20, v24
	v_cvt_pk_bf16_f32 v85, v28, v32
	v_cvt_pk_bf16_f32 v86, v36, v40
	v_cvt_pk_bf16_f32 v87, v44, v48
	v_cvt_pk_bf16_f32 v88, v52, v56
	v_cvt_pk_bf16_f32 v89, v60, v64
	v_cvt_pk_bf16_f32 v90, v68, v72
	v_cvt_pk_bf16_f32 v91, v76, v80
	v_cvt_pk_bf16_f32 v92, v21, v25
	v_cvt_pk_bf16_f32 v93, v29, v33
	v_cvt_pk_bf16_f32 v94, v37, v41
	v_cvt_pk_bf16_f32 v95, v45, v49
	v_cvt_pk_bf16_f32 v96, v53, v57
	v_cvt_pk_bf16_f32 v97, v61, v65
	v_cvt_pk_bf16_f32 v98, v69, v73
	v_cvt_pk_bf16_f32 v99, v77, v81
	v_cvt_pk_bf16_f32 v100, v22, v26
	v_cvt_pk_bf16_f32 v101, v30, v34
	v_cvt_pk_bf16_f32 v102, v38, v42
	v_cvt_pk_bf16_f32 v103, v46, v50
	v_cvt_pk_bf16_f32 v104, v54, v58
	v_cvt_pk_bf16_f32 v105, v62, v66
	v_cvt_pk_bf16_f32 v106, v70, v74
	v_cvt_pk_bf16_f32 v107, v78, v82
	v_cvt_pk_bf16_f32 v108, v23, v27
	v_cvt_pk_bf16_f32 v109, v31, v35
	v_cvt_pk_bf16_f32 v110, v39, v43
	v_cvt_pk_bf16_f32 v111, v47, v51
	v_cvt_pk_bf16_f32 v112, v55, v59
	v_cvt_pk_bf16_f32 v113, v63, v67
	v_cvt_pk_bf16_f32 v114, v71, v75
	v_cvt_pk_bf16_f32 v115, v79, v83
	global_store_dwordx4 v10, v[84:87], s[18:19]
	global_store_dwordx4 v10, v[88:91], s[18:19] offset:16
	global_store_dwordx4 v10, v[92:95], s[26:27]
	global_store_dwordx4 v10, v[96:99], s[26:27] offset:16
	global_store_dwordx4 v10, v[100:103], s[30:31]
	global_store_dwordx4 v10, v[104:107], s[30:31] offset:16
	global_store_dwordx4 v10, v[108:111], s[36:37]
	global_store_dwordx4 v10, v[112:115], s[36:37] offset:16
	s_addk_i32 s3, 0x600
	s_branch .Lew_loop_p5
; __device__ __forceinline__ int otid(int wv) { int ln; asm volatile("v_mbcnt_lo_u32_b32 %0, -1, 0\n\tv_mbcnt_hi_u32_b32 %0, -1, %0" : "=v"(ln)); return wv * 64 + ln; }
; #define G8_STAGE(bufoff, gbase, voff) do { _Pragma("unroll") for (int _i = 0; _i < 2; ++_i) \
;         __builtin_amdgcn_global_load_lds((const unsigned*)((const char*)(gbase) + (voff)[_i]), (LAS unsigned*)(lds + (bufoff) + ldsw + _i * 8192), 16, 0, 0); } while (0)
; #define G8_WAIT_V(n) asm volatile("s_waitcnt vmcnt(" #n ")" ::: "memory")
; #define G8_BAR __builtin_amdgcn_s_barrier()
; template <class Epi, class Sched>
; __device__ __forceinline__ void gemm_phase(int wv, LAS unsigned char* lds, const int K, const Sched& S, const Epi& E) {
;     const int tid = otid(wv), wid = __builtin_amdgcn_readfirstlane(tid >> 6), lane = tid & 63, wr = wid >> 2, wc = wid & 3, fr = lane & 15, fq = lane >> 4;
;     unsigned voffA[2], voffB[2];
; #pragma unroll
;     for (int i = 0; i < 2; ++i) { int R, C; stage_rc(tid * 16 + i * 8192, R, C); const int Rb = Epi::PERM ? ((R & ~31) + perm32(R & 31)) : R;
;         voffA[i] = (unsigned)(R * K + C) * 2u; voffB[i] = (unsigned)(Rb * K + C) * 2u; }
;     const size_t kstep = (size_t)(BK * 2);
;     const size_t hstep = (size_t)HALF * K * 2;
;     const unsigned ldsw = (unsigned)wid * 1024u;
;     const int aoff = lds_byte(wr * 64 + fr, fq * 8), boff = lds_byte(wc * 32 + fr, fq * 8);
;     ...
;     Unit cur, nxt; int ui = 0;
;     if (!S.next(0, cur)) return;
;     f32x4 acc[2][2][4][2];
; #pragma unroll
;     for (int a = 0; a < 2; ++a)
; #pragma unroll
;         for (int b = 0; b < 2; ++b)
; #pragma unroll
;             for (int m = 0; m < 4; ++m)
; #pragma unroll
;                 for (int n = 0; n < 2; ++n) acc[a][b][m][n] = (f32x4){0.f, 0.f, 0.f, 0.f};
;     bf16x8 At[4][2], B0[2][2], B1[2][2];
;     const char* cA = cur.a; const char* cB = cur.b;
;     G8_STAGE(G8_SB(0, 0), cB, voffB); G8_STAGE(G8_SA(0, 0), cA, voffA); G8_STAGE(G8_SB(0, 1), cB + hstep, voffB); G8_STAGE(G8_SA(0, 1), cA + hstep, voffA);
;     if (wr == 1) G8_BAR;
;     G8_WAIT_V(4); G8_BAR;
;     G8_STAGE(G8_SB(1, 0), cB + kstep, voffB); G8_STAGE(G8_SA(1, 0), cA + kstep, voffA); G8_STAGE(G8_SB(1, 1), cB + hstep + kstep, voffB);
;     G8_WAIT_V(6); G8_BAR;
.Lew_rest_p5:
	s_waitcnt vmcnt(0)
	v_readlane_b32 s3, v255, 43
	v_readlane_b32 s6, v255, 44
	v_readlane_b32 s7, v255, 45
	v_readlane_b32 s14, v255, 46
	v_readlane_b32 s15, v255, 47
	v_readlane_b32 s16, v255, 48
	v_readlane_b32 s17, v255, 49
	v_readlane_b32 s18, v255, 50
	v_readlane_b32 s19, v255, 51
	v_readlane_b32 s22, v255, 52
	v_readlane_b32 s23, v255, 53
	v_readlane_b32 s26, v255, 54
	v_readlane_b32 s27, v255, 55
	v_readlane_b32 s30, v255, 56
	v_readlane_b32 s31, v255, 57
	v_readlane_b32 s36, v255, 58
	v_readlane_b32 s37, v255, 59
.Lew_end_p5:
	v_readlane_b32 s24, v255, 63
	v_readlane_b32 s0, v255, 18
	v_readlane_b32 s1, v255, 19
	s_and_b64 s[0:1], s[0:1], exec
	s_mov_b64 s[4:5], s[90:91]
	s_cselect_b32 s28, 0x48, 64
	s_waitcnt lgkmcnt(0)
	s_barrier
	v_mbcnt_lo_u32_b32 v11, -1, 0
	v_mbcnt_hi_u32_b32 v11, -1, v11
	s_cmp_ge_i32 s96, s28
	v_add_u32_e32 v2, s89, v11
	s_nop 0
	v_readfirstlane_b32 s0, v2
	s_cbranch_scc1 .LBB0_951
	v_lshlrev_b32_e32 v3, 4, v2
	v_add_u32_e32 v4, 0x2000, v3
	v_ashrrev_i32_e32 v0, 31, v4
	v_lshrrev_b32_e32 v0, 22, v0
	v_add_u32_e32 v0, v4, v0
	v_ashrrev_i32_e32 v0, 10, v0
	v_mul_i32_i24_e32 v5, 0x400, v0
	v_sub_u32_e32 v4, v4, v5
	v_lshrrev_b32_e32 v5, 4, v4
	v_bitop3_b32 v4, v5, v4, 32 bitop3:0x6c
	v_ashrrev_i32_e32 v5, 31, v4
	v_lshrrev_b32_e32 v5, 26, v5
	v_add_u32_e32 v5, v4, v5
	v_lshlrev_b32_e32 v7, 3, v0
	v_ashrrev_i32_e32 v6, 6, v5
	v_and_b32_e32 v7, -16, v7
	v_add_u32_e32 v8, v6, v7
	v_and_b32_e32 v7, 3, v6
	s_mov_b32 s3, 0x3fffe0
	v_lshrrev_b32_e32 v9, 2, v8
	v_lshlrev_b32_e32 v10, 1, v8
	v_and_b32_e32 v5, 0xc0, v5
	v_and_or_b32 v7, v8, s3, v7
	v_and_b32_e32 v9, 4, v9
	v_and_b32_e32 v10, 24, v10
	v_sub_u32_e32 v4, v4, v5
	v_or3_b32 v9, v7, v9, v10
	v_lshlrev_b32_e32 v7, 5, v0
	v_ashrrev_i16_sdwa v4, v230, sext(v4) dst_sel:DWORD dst_unused:UNUSED_PAD src0_sel:DWORD src1_sel:BYTE_0
	v_and_b32_e32 v10, 32, v7
	v_bfe_i32 v7, v4, 0, 16
	v_add_lshl_u32 v4, v10, v7, 1
	v_lshl_add_u32 v132, v9, 10, v4
	v_lshl_add_u32 v134, v8, 10, v4
	v_bfe_i32 v4, v2, 27, 1
	v_lshrrev_b32_e32 v4, 22, v4
	v_add_u32_e32 v4, v3, v4
	v_and_b32_e32 v4, 0xfffffc00, v4
	v_sub_u32_e32 v3, v3, v4
	v_lshrrev_b32_e32 v4, 4, v3
	v_ashrrev_i32_e32 v5, 31, v2
	v_bitop3_b32 v3, v4, v3, 32 bitop3:0x6c
	v_lshrrev_b32_e32 v5, 26, v5
	v_ashrrev_i32_e32 v4, 31, v3
	v_add_u32_e32 v2, v2, v5
	v_lshrrev_b32_e32 v4, 26, v4
	v_ashrrev_i32_e32 v9, 6, v2
	v_add_u32_e32 v4, v3, v4
	v_lshlrev_b32_e32 v2, 3, v9
	v_ashrrev_i32_e32 v8, 6, v4
	v_and_b32_e32 v2, -16, v2
	v_add_u32_e32 v2, v8, v2
	v_and_b32_e32 v5, 3, v8
	s_load_dwordx2 s[8:9], s[4:5], 0xa8
	s_ashr_i32 s4, s0, 6
	v_and_or_b32 v5, v2, s3, v5
	s_lshr_b32 s3, s28, 3
	v_readlane_b32 s6, v253, 40
	s_ashr_i32 s5, s0, 8
	s_lshl_b32 s1, s4, 10
	s_add_i32 s24, s3, 1
	v_readlane_b32 s7, v253, 41
	s_and_b64 s[6:7], s[6:7], exec
	s_cselect_b32 s6, s24, s3
	v_readlane_b32 s7, v253, 39
	s_mul_i32 s6, s6, s7
	v_readlane_b32 s7, v253, 58
	s_add_i32 s10, s6, s7
	s_waitcnt lgkmcnt(0)
	s_add_u32 s25, s8, 0x8720000
	s_addc_u32 s26, s9, 0
	s_ashr_i32 s11, s10, 31
	v_lshrrev_b32_e32 v10, 2, v2
	s_waitcnt vmcnt(8)
	v_lshlrev_b32_e32 v12, 1, v2
	v_and_b32_e32 v4, 0xc0, v4
	s_lshl_b64 s[6:7], s[10:11], 18
	v_and_b32_e32 v10, 4, v10
	v_and_b32_e32 v12, 24, v12
	v_sub_u32_e32 v3, v3, v4
	s_add_u32 s16, s25, s6
	v_or3_b32 v5, v5, v10, v12
	v_lshlrev_b32_e32 v10, 5, v9
	v_ashrrev_i16_sdwa v3, v230, sext(v3) dst_sel:DWORD dst_unused:UNUSED_PAD src0_sel:DWORD src1_sel:BYTE_0
	s_addc_u32 s17, s26, s7
	v_and_b32_e32 v12, 32, v10
	v_bfe_i32 v10, v3, 0, 16
	s_add_u32 s6, s8, 0xc5cc000
	v_add_lshl_u32 v3, v12, v10, 1
	s_addc_u32 s7, s9, 0
	s_add_i32 s27, s1, 0
	v_lshl_add_u32 v136, v5, 10, v3
	s_add_i32 m0, s27, 0x10000
	v_lshl_add_u32 v138, v2, 10, v3
	global_load_lds_dwordx4 v136, s[6:7]
	s_add_i32 m0, s27, 0x12000
	s_add_i32 s30, s27, 0x2000
	global_load_lds_dwordx4 v132, s[6:7]
	s_mov_b32 m0, s27
	s_add_u32 s12, s8, 0xc5ec000
	global_load_lds_dwordx4 v138, s[16:17]
	s_mov_b32 m0, s30
	s_addc_u32 s13, s9, 0
	global_load_lds_dwordx4 v134, s[16:17]
	s_add_i32 m0, s27, 0x14000
	v_mov_b32_e32 v139, v1
	global_load_lds_dwordx4 v136, s[12:13]
	s_add_i32 m0, s27, 0x16000
	v_mov_b32_e32 v135, v1
	global_load_lds_dwordx4 v132, s[12:13]
	s_add_u32 s12, s16, 0x20000
	s_addc_u32 s13, s17, 0
	s_add_i32 s31, s27, 0x4000
	s_mov_b32 m0, s31
	s_add_i32 s34, s27, 0x6000
	global_load_lds_dwordx4 v138, s[12:13]
	s_mov_b32 m0, s34
	v_lshl_add_u64 v[4:5], s[16:17], 0, v[138:139]
	global_load_lds_dwordx4 v134, s[12:13]
	s_cmp_lg_u32 s5, 1
	v_lshl_add_u64 v[2:3], s[16:17], 0, v[134:135]
	s_cbranch_scc1 .LBB0_942
	s_barrier
